# P0: w_in transpose loads de-serialised (32 W + 32 norm_g loads in flight, counted vmcnt)
# speedup vs baseline: 1.0215x; 1.0215x over previous
.LBB0_34:
	s_andn2_saveexec_b64 s[8:9], s[0:1]
	s_cbranch_execz .LBB0_11
	v_mul_hi_i32 v4, v72, s82
	v_add_u32_e32 v4, v4, v72
	v_lshrrev_b32_e32 v26, 31, v4
	v_ashrrev_i32_e32 v4, 7, v4
	v_add_u32_e32 v4, v4, v26
	v_mul_lo_u32 v26, v4, s83
	v_sub_u32_e32 v26, v72, v26
	v_lshlrev_b32_e32 v26, 5, v26
	v_lshlrev_b32_e32 v28, 6, v4
	v_ashrrev_i32_e32 v27, 31, v26
	v_or_b32_e32 v4, v60, v28
	v_lshlrev_b64 v[50:51], 2, v[26:27]
	v_mad_i64_i32 v[30:31], s[0:1], v4, s84, v[50:51]
	v_or_b32_e32 v4, v62, v28
	v_mad_i64_i32 v[34:35], s[0:1], v4, s84, v[50:51]
	v_or_b32_e32 v4, v63, v28
	v_mad_i64_i32 v[36:37], s[0:1], v4, s84, v[50:51]
	v_or_b32_e32 v4, v64, v28
	v_ashrrev_i32_e32 v29, 31, v28
	v_mad_i64_i32 v[38:39], s[0:1], v4, s84, v[50:51]
	v_or_b32_e32 v4, v65, v28
	v_or_b32_e32 v48, v2, v28
	v_mov_b32_e32 v49, v29
	v_mad_i64_i32 v[40:41], s[0:1], v4, s84, v[50:51]
	v_or_b32_e32 v4, v66, v28
	v_lshlrev_b64 v[32:33], 2, v[48:49]
	v_mad_i64_i32 v[42:43], s[0:1], v4, s84, v[50:51]
	v_or_b32_e32 v4, v67, v28
	v_ashrrev_i32_e32 v49, 31, v48
	v_mad_i64_i32 v[44:45], s[0:1], v4, s84, v[50:51]
	v_lshlrev_b64 v[46:47], 2, v[48:49]
	v_mad_i64_i32 v[48:49], s[0:1], v48, s84, v[50:51]
	v_lshl_add_u64 v[30:31], v[24:25], 0, v[30:31]
	v_lshl_add_u64 v[34:35], v[24:25], 0, v[34:35]
	v_lshl_add_u64 v[36:37], v[24:25], 0, v[36:37]
	v_lshl_add_u64 v[38:39], v[24:25], 0, v[38:39]
	v_lshl_add_u64 v[40:41], v[24:25], 0, v[40:41]
	v_lshl_add_u64 v[42:43], v[24:25], 0, v[42:43]
	v_lshl_add_u64 v[44:45], v[24:25], 0, v[44:45]
	v_lshl_add_u64 v[48:49], v[24:25], 0, v[48:49]
	s_andn2_b64 vcc, exec, s[70:71]
	s_cbranch_vccnz .Lp0_win_orig
	v_lshl_add_u64 v[76:77], s[54:55], 0, v[32:33]
	s_mov_b64 s[38:39], 0
	v_lshl_add_u64 v[74:75], v[48:49], 0, s[38:39]
	global_load_dword v140, v[74:75], off nt
	v_lshl_add_u64 v[78:79], v[44:45], 0, s[38:39]
	global_load_dword v141, v[78:79], off nt
	v_lshl_add_u64 v[74:75], v[42:43], 0, s[38:39]
	global_load_dword v142, v[74:75], off nt
	v_lshl_add_u64 v[78:79], v[40:41], 0, s[38:39]
	global_load_dword v143, v[78:79], off nt
	v_lshl_add_u64 v[74:75], v[38:39], 0, s[38:39]
	global_load_dword v144, v[74:75], off nt
	v_lshl_add_u64 v[78:79], v[36:37], 0, s[38:39]
	global_load_dword v145, v[78:79], off nt
	v_lshl_add_u64 v[74:75], v[34:35], 0, s[38:39]
	global_load_dword v146, v[74:75], off nt
	v_lshl_add_u64 v[78:79], v[30:31], 0, s[38:39]
	global_load_dword v147, v[78:79], off nt
	s_add_u32 s38, s38, 0x70000
	s_addc_u32 s39, s39, 0
	v_lshl_add_u64 v[74:75], v[48:49], 0, s[38:39]
	global_load_dword v148, v[74:75], off nt
	v_lshl_add_u64 v[78:79], v[44:45], 0, s[38:39]
	global_load_dword v149, v[78:79], off nt
	v_lshl_add_u64 v[74:75], v[42:43], 0, s[38:39]
	global_load_dword v150, v[74:75], off nt
	v_lshl_add_u64 v[78:79], v[40:41], 0, s[38:39]
	global_load_dword v151, v[78:79], off nt
	v_lshl_add_u64 v[74:75], v[38:39], 0, s[38:39]
	global_load_dword v152, v[74:75], off nt
	v_lshl_add_u64 v[78:79], v[36:37], 0, s[38:39]
	global_load_dword v153, v[78:79], off nt
	v_lshl_add_u64 v[74:75], v[34:35], 0, s[38:39]
	global_load_dword v154, v[74:75], off nt
	v_lshl_add_u64 v[78:79], v[30:31], 0, s[38:39]
	global_load_dword v155, v[78:79], off nt
	s_add_u32 s38, s38, 0x70000
	s_addc_u32 s39, s39, 0
	v_lshl_add_u64 v[74:75], v[48:49], 0, s[38:39]
	global_load_dword v156, v[74:75], off nt
	v_lshl_add_u64 v[78:79], v[44:45], 0, s[38:39]
	global_load_dword v157, v[78:79], off nt
	v_lshl_add_u64 v[74:75], v[42:43], 0, s[38:39]
	global_load_dword v158, v[74:75], off nt
	v_lshl_add_u64 v[78:79], v[40:41], 0, s[38:39]
	global_load_dword v159, v[78:79], off nt
	v_lshl_add_u64 v[74:75], v[38:39], 0, s[38:39]
	global_load_dword v160, v[74:75], off nt
	v_lshl_add_u64 v[78:79], v[36:37], 0, s[38:39]
	global_load_dword v161, v[78:79], off nt
	v_lshl_add_u64 v[74:75], v[34:35], 0, s[38:39]
	global_load_dword v162, v[74:75], off nt
	v_lshl_add_u64 v[78:79], v[30:31], 0, s[38:39]
	global_load_dword v163, v[78:79], off nt
	s_add_u32 s38, s38, 0x70000
	s_addc_u32 s39, s39, 0
	v_lshl_add_u64 v[74:75], v[48:49], 0, s[38:39]
	global_load_dword v164, v[74:75], off nt
	v_lshl_add_u64 v[78:79], v[44:45], 0, s[38:39]
	global_load_dword v165, v[78:79], off nt
	v_lshl_add_u64 v[74:75], v[42:43], 0, s[38:39]
	global_load_dword v166, v[74:75], off nt
	v_lshl_add_u64 v[78:79], v[40:41], 0, s[38:39]
	global_load_dword v167, v[78:79], off nt
	v_lshl_add_u64 v[74:75], v[38:39], 0, s[38:39]
	global_load_dword v168, v[74:75], off nt
	v_lshl_add_u64 v[78:79], v[36:37], 0, s[38:39]
	global_load_dword v169, v[78:79], off nt
	v_lshl_add_u64 v[74:75], v[34:35], 0, s[38:39]
	global_load_dword v170, v[74:75], off nt
	v_lshl_add_u64 v[78:79], v[30:31], 0, s[38:39]
	global_load_dword v171, v[78:79], off nt
	global_load_dword v172, v[76:77], off
	global_load_dword v173, v[76:77], off offset:8
	global_load_dword v174, v[76:77], off offset:16
	global_load_dword v175, v[76:77], off offset:24
	global_load_dword v176, v[76:77], off offset:32
	global_load_dword v177, v[76:77], off offset:40
	global_load_dword v178, v[76:77], off offset:48
	global_load_dword v179, v[76:77], off offset:56
	global_load_dword v180, v[76:77], off offset:64
	global_load_dword v181, v[76:77], off offset:72
	global_load_dword v182, v[76:77], off offset:80
	global_load_dword v183, v[76:77], off offset:88
	global_load_dword v184, v[76:77], off offset:96
	global_load_dword v185, v[76:77], off offset:104
	global_load_dword v186, v[76:77], off offset:112
	global_load_dword v187, v[76:77], off offset:120
	global_load_dword v188, v[76:77], off offset:128
	global_load_dword v189, v[76:77], off offset:136
	global_load_dword v190, v[76:77], off offset:144
	global_load_dword v191, v[76:77], off offset:152
	global_load_dword v192, v[76:77], off offset:160
	global_load_dword v193, v[76:77], off offset:168
	global_load_dword v194, v[76:77], off offset:176
	global_load_dword v195, v[76:77], off offset:184
	global_load_dword v196, v[76:77], off offset:192
	global_load_dword v197, v[76:77], off offset:200
	global_load_dword v198, v[76:77], off offset:208
	global_load_dword v199, v[76:77], off offset:216
	global_load_dword v200, v[76:77], off offset:224
	global_load_dword v201, v[76:77], off offset:232
	global_load_dword v202, v[76:77], off offset:240
	global_load_dword v203, v[76:77], off offset:248
	s_waitcnt vmcnt(31)
	v_mul_f32_e32 v140, v140, v172
	ds_write_b32 v58, v140
	s_waitcnt vmcnt(30)
	v_mul_f32_e32 v141, v141, v173
	ds_write_b32 v58, v141 offset:264
	s_waitcnt vmcnt(29)
	v_mul_f32_e32 v142, v142, v174
	ds_write_b32 v58, v142 offset:528
	s_waitcnt vmcnt(28)
	v_mul_f32_e32 v143, v143, v175
	ds_write_b32 v58, v143 offset:792
	s_waitcnt vmcnt(27)
	v_mul_f32_e32 v144, v144, v176
	ds_write_b32 v58, v144 offset:1056
	s_waitcnt vmcnt(26)
	v_mul_f32_e32 v145, v145, v177
	ds_write_b32 v58, v145 offset:1320
	s_waitcnt vmcnt(25)
	v_mul_f32_e32 v146, v146, v178
	ds_write_b32 v58, v146 offset:1584
	s_waitcnt vmcnt(24)
	v_mul_f32_e32 v147, v147, v179
	ds_write_b32 v58, v147 offset:1848
	s_waitcnt vmcnt(23)
	v_mul_f32_e32 v148, v148, v180
	ds_write_b32 v58, v148 offset:2112
	s_waitcnt vmcnt(22)
	v_mul_f32_e32 v149, v149, v181
	ds_write_b32 v58, v149 offset:2376
	s_waitcnt vmcnt(21)
	v_mul_f32_e32 v150, v150, v182
	ds_write_b32 v58, v150 offset:2640
	s_waitcnt vmcnt(20)
	v_mul_f32_e32 v151, v151, v183
	ds_write_b32 v58, v151 offset:2904
	s_waitcnt vmcnt(19)
	v_mul_f32_e32 v152, v152, v184
	ds_write_b32 v58, v152 offset:3168
	s_waitcnt vmcnt(18)
	v_mul_f32_e32 v153, v153, v185
	ds_write_b32 v58, v153 offset:3432
	s_waitcnt vmcnt(17)
	v_mul_f32_e32 v154, v154, v186
	ds_write_b32 v58, v154 offset:3696
	s_waitcnt vmcnt(16)
	v_mul_f32_e32 v155, v155, v187
	ds_write_b32 v58, v155 offset:3960
	s_waitcnt vmcnt(15)
	v_mul_f32_e32 v156, v156, v188
	ds_write_b32 v58, v156 offset:4224
	s_waitcnt vmcnt(14)
	v_mul_f32_e32 v157, v157, v189
	ds_write_b32 v58, v157 offset:4488
	s_waitcnt vmcnt(13)
	v_mul_f32_e32 v158, v158, v190
	ds_write_b32 v58, v158 offset:4752
	s_waitcnt vmcnt(12)
	v_mul_f32_e32 v159, v159, v191
	ds_write_b32 v58, v159 offset:5016
	s_waitcnt vmcnt(11)
	v_mul_f32_e32 v160, v160, v192
	ds_write_b32 v58, v160 offset:5280
	s_waitcnt vmcnt(10)
	v_mul_f32_e32 v161, v161, v193
	ds_write_b32 v58, v161 offset:5544
	s_waitcnt vmcnt(9)
	v_mul_f32_e32 v162, v162, v194
	ds_write_b32 v58, v162 offset:5808
	s_waitcnt vmcnt(8)
	v_mul_f32_e32 v163, v163, v195
	ds_write_b32 v58, v163 offset:6072
	s_waitcnt vmcnt(7)
	v_mul_f32_e32 v164, v164, v196
	ds_write_b32 v58, v164 offset:6336
	s_waitcnt vmcnt(6)
	v_mul_f32_e32 v165, v165, v197
	ds_write_b32 v58, v165 offset:6600
	s_waitcnt vmcnt(5)
	v_mul_f32_e32 v166, v166, v198
	ds_write_b32 v58, v166 offset:6864
	s_waitcnt vmcnt(4)
	v_mul_f32_e32 v167, v167, v199
	ds_write_b32 v58, v167 offset:7128
	s_waitcnt vmcnt(3)
	v_mul_f32_e32 v168, v168, v200
	ds_write_b32 v58, v168 offset:7392
	s_waitcnt vmcnt(2)
	v_mul_f32_e32 v169, v169, v201
	ds_write_b32 v58, v169 offset:7656
	s_waitcnt vmcnt(1)
	v_mul_f32_e32 v170, v170, v202
	ds_write_b32 v58, v170 offset:7920
	s_waitcnt vmcnt(0)
	v_mul_f32_e32 v171, v171, v203
	ds_write_b32 v58, v171 offset:8184
	s_branch .LBB0_10
.Lp0_win_orig:
	s_mov_b64 s[38:39], 0
	s_mov_b64 s[42:43], s[54:55]
	v_mov_b32_e32 v4, v58
	s_branch .LBB0_37
